# attention unit start: 4 compressed-K/V staging loads + 4 q loads in flight before the first wait; compressed-branch K-fragment ds_reads 6 deep through a register ring
# speedup vs baseline: 1.0036x; 1.0036x over previous
.LBB0_944:
	s_bfe_u32 s0, s94, 0x40004
	s_xor_b32 s1, s0, 31
	s_cmpk_lt_i32 s94, 0x100
	s_cselect_b32 s22, s1, s0
	s_bfe_u32 s23, s94, 0x30001
	s_and_b32 s24, s94, 1
	s_lshl_b32 s1, s24, 14
	s_lshl_b32 s2, s23, 15
	s_or_b32 s2, s2, s1
	v_lshl_add_u64 v[6:7], v[112:113], 0, s[2:3]
	v_lshl_add_u64 v[2:3], v[6:7], 0, v[124:125]
	global_load_dwordx4 v[96:99], v[2:3], off
	v_lshl_add_u64 v[8:9], v[114:115], 0, s[2:3]
	v_lshl_add_u64 v[2:3], v[8:9], 0, v[124:125]
	global_load_dwordx4 v[100:103], v[2:3], off
	v_lshl_add_u64 v[2:3], v[6:7], 0, v[126:127]
	global_load_dwordx4 v[104:107], v[2:3], off
	v_lshl_add_u64 v[2:3], v[8:9], 0, v[126:127]
	global_load_dwordx4 v[108:111], v[2:3], off
	v_add_u32_e32 v0, v123, v134
	s_lshl_b32 s0, s24, 2
	v_lshl_or_b32 v243, s22, 6, v232
	s_add_i32 s2, s0, s96
	v_lshl_or_b32 v244, s23, 11, v243
	v_lshlrev_b32_e32 v128, 10, v244
	v_mov_b32_e32 v129, v1
	s_lshl_b32 s88, s2, 6
	s_ashr_i32 s89, s88, 31
	s_mov_b32 s0, 0xf149f2ca
	v_lshl_add_u64 v[2:3], s[82:83], 0, v[128:129]
	v_lshl_add_u64 v[2:3], s[88:89], 1, v[2:3]
	v_lshl_add_u64 v[2:3], v[116:117], 1, v[2:3]
	global_load_dwordx4 v[80:83], v[2:3], off
	global_load_dwordx4 v[84:87], v[2:3], off offset:32
	global_load_dwordx4 v[88:91], v[2:3], off offset:64
	global_load_dwordx4 v[92:95], v[2:3], off offset:96
	s_waitcnt vmcnt(7)
	ds_write_b128 v0, v[96:99] offset:21504
	s_nop 0
	v_add_u32_e32 v0, v123, v135
	s_waitcnt vmcnt(6)
	ds_write_b128 v0, v[100:103] offset:39936
	s_nop 0
	v_subrev_u32_e32 v0, 31, v243
	v_ashrrev_i32_e32 v0, 4, v0
	v_cmp_le_i32_e32 vcc, v118, v0
	s_waitcnt vmcnt(5)
	ds_write_b128 v233, v[104:107] offset:21504
	s_waitcnt vmcnt(4)
	ds_write_b128 v234, v[108:111] offset:39936
	s_waitcnt lgkmcnt(0)
	s_barrier
	ds_read_b128 v[66:69], v235 offset:21504
	ds_read_b128 v[70:73], v235 offset:21536
	ds_read_b128 v[74:77], v235 offset:21568
	ds_read_b128 v[96:99], v235 offset:21600
	ds_read_b128 v[100:103], v235 offset:26112
	ds_read_b128 v[104:107], v235 offset:26144
	s_waitcnt vmcnt(3)
	s_waitcnt lgkmcnt(5)
	v_mfma_f32_32x32x16_bf16 v[50:65], v[66:69], v[80:83], 0
	ds_read_b128 v[66:69], v235 offset:26176
	s_waitcnt vmcnt(2)
	s_waitcnt lgkmcnt(5)
	v_mfma_f32_32x32x16_bf16 v[50:65], v[70:73], v[84:87], v[50:65]
	ds_read_b128 v[70:73], v235 offset:26208
	s_waitcnt vmcnt(1)
	s_waitcnt lgkmcnt(5)
	v_mfma_f32_32x32x16_bf16 v[50:65], v[74:77], v[88:91], v[50:65]
	ds_read_b128 v[74:77], v235 offset:30720
	s_waitcnt vmcnt(0)
	s_waitcnt lgkmcnt(5)
	v_mfma_f32_32x32x16_bf16 v[50:65], v[96:99], v[92:95], v[50:65]
	ds_read_b128 v[96:99], v235 offset:30752
	s_waitcnt lgkmcnt(5)
	v_mfma_f32_32x32x16_bf16 v[34:49], v[100:103], v[80:83], 0
	ds_read_b128 v[100:103], v235 offset:30784
	s_nop 7
	v_cndmask_b32_e32 v50, v236, v50, vcc
	v_cmp_lt_i32_e32 vcc, v118, v0
	s_nop 1
	v_cndmask_b32_e32 v51, v236, v51, vcc
	v_cmp_le_i32_e32 vcc, v137, v0
	s_waitcnt lgkmcnt(5)
	v_mfma_f32_32x32x16_bf16 v[34:49], v[104:107], v[84:87], v[34:49]
	ds_read_b128 v[104:107], v235 offset:30816
	v_cndmask_b32_e32 v52, v236, v52, vcc
	v_cmp_le_i32_e32 vcc, v138, v0
	s_nop 1
	v_cndmask_b32_e32 v53, v236, v53, vcc
	v_cmp_le_i32_e32 vcc, v139, v0
	s_waitcnt lgkmcnt(5)
	v_mfma_f32_32x32x16_bf16 v[34:49], v[66:69], v[88:91], v[34:49]
	ds_read_b128 v[66:69], v235 offset:35328
	v_cndmask_b32_e32 v54, v236, v54, vcc
	v_cmp_le_i32_e32 vcc, v140, v0
	s_nop 1
	v_cndmask_b32_e32 v55, v236, v55, vcc
	v_cmp_le_i32_e32 vcc, v141, v0
	s_waitcnt lgkmcnt(5)
	v_mfma_f32_32x32x16_bf16 v[34:49], v[70:73], v[92:95], v[34:49]
	ds_read_b128 v[70:73], v235 offset:35360
	s_waitcnt lgkmcnt(5)
	v_mfma_f32_32x32x16_bf16 v[18:33], v[74:77], v[80:83], 0
	ds_read_b128 v[74:77], v235 offset:35392
	s_waitcnt lgkmcnt(5)
	v_mfma_f32_32x32x16_bf16 v[18:33], v[96:99], v[84:87], v[18:33]
	ds_read_b128 v[96:99], v235 offset:35424
	s_waitcnt lgkmcnt(5)
	v_mfma_f32_32x32x16_bf16 v[18:33], v[100:103], v[88:91], v[18:33]
	s_waitcnt lgkmcnt(4)
	v_mfma_f32_32x32x16_bf16 v[18:33], v[104:107], v[92:95], v[18:33]
	s_waitcnt lgkmcnt(3)
	v_mfma_f32_32x32x16_bf16 v[2:17], v[66:69], v[80:83], 0
	s_waitcnt lgkmcnt(2)
	v_mfma_f32_32x32x16_bf16 v[2:17], v[70:73], v[84:87], v[2:17]
	s_waitcnt lgkmcnt(1)
	v_mfma_f32_32x32x16_bf16 v[2:17], v[74:77], v[88:91], v[2:17]
	s_waitcnt lgkmcnt(0)
	v_mfma_f32_32x32x16_bf16 v[2:17], v[96:99], v[92:95], v[2:17]
	v_max3_f32 v66, v50, s0, v51
	v_max3_f32 v66, v66, v52, v53
	v_cndmask_b32_e32 v67, v236, v56, vcc
	v_cmp_le_i32_e32 vcc, v142, v0
	v_max3_f32 v66, v66, v54, v55
	s_nop 0
	v_cndmask_b32_e32 v68, v236, v57, vcc
	v_cmp_le_i32_e32 vcc, v143, v0
	v_max3_f32 v56, v66, v67, v68
	s_nop 0
	v_cndmask_b32_e32 v66, v236, v58, vcc
	v_cmp_le_i32_e32 vcc, v144, v0
	s_nop 1
	v_cndmask_b32_e32 v69, v236, v59, vcc
	v_cmp_le_i32_e32 vcc, v145, v0
	v_max3_f32 v56, v56, v66, v69
	s_nop 0
	v_cndmask_b32_e32 v70, v236, v60, vcc
	v_cmp_le_i32_e32 vcc, v146, v0
	s_nop 1
	v_cndmask_b32_e32 v71, v236, v61, vcc
	v_cmp_le_i32_e32 vcc, v147, v0
	v_max3_f32 v56, v56, v70, v71
	s_nop 0
	v_cndmask_b32_e32 v72, v236, v62, vcc
	v_cmp_le_i32_e32 vcc, v148, v0
	s_nop 1
	v_cndmask_b32_e32 v73, v236, v63, vcc
	v_cmp_le_i32_e32 vcc, v149, v0
	v_max3_f32 v56, v56, v72, v73
	s_nop 0
	v_cndmask_b32_e32 v74, v236, v64, vcc
	v_cmp_le_i32_e32 vcc, v150, v0
	s_nop 1
	v_cndmask_b32_e32 v75, v236, v65, vcc
	v_cmp_le_i32_e32 vcc, v151, v0
	v_max3_f32 v56, v56, v74, v75
	s_nop 0
	v_cndmask_b32_e32 v34, v236, v34, vcc
	v_cmp_lt_i32_e32 vcc, v151, v0
	s_nop 1
	v_cndmask_b32_e32 v35, v236, v35, vcc
	v_cmp_le_i32_e32 vcc, v152, v0
	v_max3_f32 v56, v56, v34, v35
	s_nop 0
	v_cndmask_b32_e32 v36, v236, v36, vcc
	v_cmp_le_i32_e32 vcc, v153, v0
	s_nop 1
	v_cndmask_b32_e32 v37, v236, v37, vcc
	v_cmp_le_i32_e32 vcc, v154, v0
	v_max3_f32 v56, v56, v36, v37
	s_nop 0
	v_cndmask_b32_e32 v38, v236, v38, vcc
	v_cmp_le_i32_e32 vcc, v155, v0
	s_nop 1
	v_cndmask_b32_e32 v39, v236, v39, vcc
	v_cmp_le_i32_e32 vcc, v156, v0
	v_max3_f32 v56, v56, v38, v39
	s_nop 0
	v_cndmask_b32_e32 v40, v236, v40, vcc
	v_cmp_le_i32_e32 vcc, v157, v0
	s_nop 1
	v_cndmask_b32_e32 v41, v236, v41, vcc
	v_cmp_le_i32_e32 vcc, v158, v0
	v_max3_f32 v56, v56, v40, v41
	s_nop 0
	v_cndmask_b32_e32 v42, v236, v42, vcc
	v_cmp_le_i32_e32 vcc, v159, v0
	s_nop 1
	v_cndmask_b32_e32 v43, v236, v43, vcc
	v_cmp_le_i32_e32 vcc, v160, v0
	v_max3_f32 v56, v56, v42, v43
	s_nop 0
	v_cndmask_b32_e32 v44, v236, v44, vcc
	v_cmp_le_i32_e32 vcc, v161, v0
	s_nop 1
	v_cndmask_b32_e32 v45, v236, v45, vcc
	v_cmp_le_i32_e32 vcc, v162, v0
	v_max3_f32 v56, v56, v44, v45
	s_nop 0
	v_cndmask_b32_e32 v46, v236, v46, vcc
	v_cmp_le_i32_e32 vcc, v163, v0
	s_nop 1
	v_cndmask_b32_e32 v47, v236, v47, vcc
	v_cmp_le_i32_e32 vcc, v164, v0
	v_max3_f32 v56, v56, v46, v47
	s_nop 0
	v_cndmask_b32_e32 v48, v236, v48, vcc
	v_cmp_le_i32_e32 vcc, v165, v0
	s_nop 1
	v_cndmask_b32_e32 v49, v236, v49, vcc
	v_cmp_le_i32_e32 vcc, v166, v0
	v_max3_f32 v56, v56, v48, v49
	s_nop 0
	v_cndmask_b32_e32 v76, v236, v18, vcc
	v_cmp_lt_i32_e32 vcc, v166, v0
	s_nop 1
	v_cndmask_b32_e32 v77, v236, v19, vcc
	v_cmp_le_i32_e32 vcc, v167, v0
	v_max3_f32 v18, v56, v76, v77
	s_nop 0
	v_cndmask_b32_e32 v78, v236, v20, vcc
	v_cmp_le_i32_e32 vcc, v168, v0
	s_nop 1
	v_cndmask_b32_e32 v79, v236, v21, vcc
	v_cmp_le_i32_e32 vcc, v169, v0
	v_max3_f32 v18, v18, v78, v79
	s_nop 0
	v_cndmask_b32_e32 v96, v236, v22, vcc
	v_cmp_le_i32_e32 vcc, v170, v0
	s_nop 1
	v_cndmask_b32_e32 v97, v236, v23, vcc
	v_cmp_le_i32_e32 vcc, v171, v0
	v_max3_f32 v18, v18, v96, v97
	s_nop 0
	v_cndmask_b32_e32 v98, v236, v24, vcc
	v_cmp_le_i32_e32 vcc, v172, v0
	s_nop 1
	v_cndmask_b32_e32 v99, v236, v25, vcc
	v_cmp_le_i32_e32 vcc, v173, v0
	v_max3_f32 v18, v18, v98, v99
	s_nop 0
	v_cndmask_b32_e32 v100, v236, v26, vcc
	v_cmp_le_i32_e32 vcc, v174, v0
	s_nop 1
	v_cndmask_b32_e32 v101, v236, v27, vcc
	v_cmp_le_i32_e32 vcc, v175, v0
	v_max3_f32 v18, v18, v100, v101
	s_nop 0
	v_cndmask_b32_e32 v102, v236, v28, vcc
	v_cmp_le_i32_e32 vcc, v176, v0
	s_nop 1
	v_cndmask_b32_e32 v103, v236, v29, vcc
	v_cmp_le_i32_e32 vcc, v177, v0
	v_max3_f32 v18, v18, v102, v103
	s_nop 0
	v_cndmask_b32_e32 v104, v236, v30, vcc
	v_cmp_le_i32_e32 vcc, v178, v0
	s_nop 1
	v_cndmask_b32_e32 v105, v236, v31, vcc
	v_cmp_le_i32_e32 vcc, v179, v0
	v_max3_f32 v18, v18, v104, v105
	s_nop 0
	v_cndmask_b32_e32 v106, v236, v32, vcc
	v_cmp_le_i32_e32 vcc, v180, v0
	s_nop 1
	v_cndmask_b32_e32 v107, v236, v33, vcc
	v_cmp_le_i32_e32 vcc, v181, v0
	v_max3_f32 v18, v18, v106, v107
	s_nop 0
	v_cndmask_b32_e32 v108, v236, v2, vcc
	v_cmp_lt_i32_e32 vcc, v181, v0
	s_nop 1
	v_cndmask_b32_e32 v109, v236, v3, vcc
	v_cmp_le_i32_e32 vcc, v182, v0
	v_max3_f32 v2, v18, v108, v109
	s_nop 0
	v_cndmask_b32_e32 v110, v236, v4, vcc
	v_cmp_le_i32_e32 vcc, v183, v0
	s_nop 1
	v_cndmask_b32_e32 v111, v236, v5, vcc
	v_cmp_le_i32_e32 vcc, v184, v0
	v_max3_f32 v2, v2, v110, v111
	s_nop 0
	v_cndmask_b32_e32 v129, v236, v6, vcc
	v_cmp_le_i32_e32 vcc, v185, v0
	s_nop 1
	v_cndmask_b32_e32 v130, v236, v7, vcc
	v_cmp_le_i32_e32 vcc, v186, v0
	v_max3_f32 v2, v2, v129, v130
	s_nop 0
	v_cndmask_b32_e32 v56, v236, v8, vcc
	v_cmp_le_i32_e32 vcc, v187, v0
	s_nop 1
	v_cndmask_b32_e32 v57, v236, v9, vcc
	v_cmp_le_i32_e32 vcc, v188, v0
	v_max3_f32 v2, v2, v56, v57
	s_nop 0
	v_cndmask_b32_e32 v58, v236, v10, vcc
	v_cmp_le_i32_e32 vcc, v189, v0
	s_nop 1
	v_cndmask_b32_e32 v59, v236, v11, vcc
	v_cmp_le_i32_e32 vcc, v190, v0
	v_max3_f32 v2, v2, v58, v59
	s_nop 0
	v_cndmask_b32_e32 v62, v236, v12, vcc
	v_cmp_le_i32_e32 vcc, v191, v0
	s_nop 1
	v_cndmask_b32_e32 v63, v236, v13, vcc
	v_cmp_le_i32_e32 vcc, v192, v0
	v_max3_f32 v2, v2, v62, v63
	s_nop 0
	v_cndmask_b32_e32 v65, v236, v14, vcc
	v_cmp_le_i32_e32 vcc, v193, v0
	s_nop 1
	v_cndmask_b32_e32 v64, v236, v15, vcc
	v_cmp_le_i32_e32 vcc, v194, v0
	v_max3_f32 v2, v2, v65, v64
	s_nop 0
	v_cndmask_b32_e32 v61, v236, v16, vcc
	v_cmp_le_i32_e32 vcc, v195, v0
	s_nop 1
	v_cndmask_b32_e32 v0, v236, v17, vcc
	v_max3_f32 v2, v2, v61, v0
	ds_bpermute_b32 v3, v196, v2
	v_cmp_lt_u32_e32 vcc, 30, v243
	s_waitcnt lgkmcnt(0)
	v_max_f32_e32 v3, v3, v3
	v_max_f32_e32 v60, v2, v3
	v_sub_f32_e32 v2, v50, v60
	v_exp_f32_e32 v2, v2
	v_sub_f32_e32 v3, v51, v60
	v_exp_f32_e32 v3, v3
	v_sub_f32_e32 v13, v70, v60
	v_add_f32_e32 v4, 0, v2
	v_exp_f32_e32 v14, v13
	v_add_f32_e32 v5, v3, v4
	v_sub_f32_e32 v4, v52, v60
	v_exp_f32_e32 v4, v4
	v_sub_f32_e32 v13, v71, v60
	v_exp_f32_e32 v15, v13
	v_sub_f32_e32 v13, v72, v60
	v_add_f32_e32 v6, v4, v5
	v_sub_f32_e32 v5, v53, v60
	v_exp_f32_e32 v5, v5
	v_exp_f32_e32 v18, v13
	v_sub_f32_e32 v13, v73, v60
	v_exp_f32_e32 v19, v13
	v_add_f32_e32 v7, v5, v6
	v_sub_f32_e32 v6, v54, v60
	v_exp_f32_e32 v6, v6
	v_sub_f32_e32 v13, v74, v60
	v_exp_f32_e32 v20, v13
	v_sub_f32_e32 v13, v75, v60
	v_add_f32_e32 v8, v6, v7
	v_sub_f32_e32 v7, v55, v60
	v_exp_f32_e32 v7, v7
	v_exp_f32_e32 v21, v13
	v_sub_f32_e32 v29, v44, v60
	v_exp_f32_e32 v30, v29
	v_add_f32_e32 v9, v7, v8
	v_sub_f32_e32 v8, v67, v60
	v_exp_f32_e32 v8, v8
	v_sub_f32_e32 v29, v45, v60
	v_exp_f32_e32 v31, v29
	v_sub_f32_e32 v29, v46, v60
	v_add_f32_e32 v10, v8, v9
	v_sub_f32_e32 v9, v68, v60
	v_exp_f32_e32 v9, v9
	v_sub_f32_e32 v45, v102, v60
	v_exp_f32_e32 v46, v45
	v_sub_f32_e32 v45, v103, v60
	v_add_f32_e32 v11, v9, v10
	v_sub_f32_e32 v10, v66, v60
	v_exp_f32_e32 v10, v10
	v_sub_f32_e32 v56, v56, v60
	v_exp_f32_e32 v56, v56
	v_sub_f32_e32 v57, v57, v60
	v_add_f32_e32 v12, v10, v11
	v_sub_f32_e32 v11, v69, v60
	v_exp_f32_e32 v11, v11
	v_exp_f32_e32 v57, v57
	v_sub_f32_e32 v58, v58, v60
	v_exp_f32_e32 v58, v58
	v_add_f32_e32 v12, v11, v12
	v_add_f32_e32 v12, v14, v12
	v_add_f32_e32 v12, v15, v12
	v_add_f32_e32 v12, v18, v12
	v_add_f32_e32 v12, v19, v12
	v_add_f32_e32 v12, v20, v12
	v_add_f32_e32 v13, v21, v12
	v_sub_f32_e32 v12, v34, v60
	v_exp_f32_e32 v12, v12
	v_exp_f32_e32 v34, v29
	v_sub_f32_e32 v29, v47, v60
	v_exp_f32_e32 v47, v45
	v_add_f32_e32 v16, v12, v13
	v_sub_f32_e32 v13, v35, v60
	v_exp_f32_e32 v13, v13
	v_exp_f32_e32 v35, v29
	v_sub_f32_e32 v29, v48, v60
	v_sub_f32_e32 v45, v104, v60
	v_add_f32_e32 v17, v13, v16
	v_sub_f32_e32 v16, v36, v60
	v_exp_f32_e32 v16, v16
	v_exp_f32_e32 v36, v29
	v_sub_f32_e32 v29, v49, v60
	v_exp_f32_e32 v50, v45
	v_add_f32_e32 v22, v16, v17
	v_sub_f32_e32 v17, v37, v60
	v_exp_f32_e32 v17, v17
	v_exp_f32_e32 v37, v29
	v_sub_f32_e32 v45, v105, v60
	v_exp_f32_e32 v51, v45
	v_add_f32_e32 v23, v17, v22
	v_sub_f32_e32 v22, v38, v60
	v_exp_f32_e32 v22, v22
	v_sub_f32_e32 v45, v106, v60
	v_exp_f32_e32 v52, v45
	v_sub_f32_e32 v45, v107, v60
	v_add_f32_e32 v24, v22, v23
	v_sub_f32_e32 v23, v39, v60
	v_exp_f32_e32 v23, v23
	v_exp_f32_e32 v53, v45
	v_sub_f32_e32 v59, v59, v60
	v_exp_f32_e32 v59, v59
	v_add_f32_e32 v25, v23, v24
	v_sub_f32_e32 v24, v40, v60
	v_exp_f32_e32 v24, v24
	v_sub_f32_e32 v62, v62, v60
	v_exp_f32_e32 v62, v62
	v_sub_f32_e32 v63, v63, v60
	v_add_f32_e32 v26, v24, v25
	v_sub_f32_e32 v25, v41, v60
	v_exp_f32_e32 v25, v25
	v_exp_f32_e32 v63, v63
	v_sub_f32_e32 v65, v65, v60
	v_sub_f32_e32 v64, v64, v60
	v_add_f32_e32 v27, v25, v26
	v_sub_f32_e32 v26, v42, v60
	v_exp_f32_e32 v26, v26
	v_sub_f32_e32 v61, v61, v60
	v_sub_f32_e32 v0, v0, v60
	v_add_f32_e32 v28, v26, v27
	v_sub_f32_e32 v27, v43, v60
	v_exp_f32_e32 v27, v27
	s_nop 0
	v_add_f32_e32 v28, v27, v28
	v_add_f32_e32 v28, v30, v28
	v_add_f32_e32 v28, v31, v28
	v_add_f32_e32 v28, v34, v28
	v_add_f32_e32 v28, v35, v28
	v_add_f32_e32 v28, v36, v28
	v_add_f32_e32 v29, v37, v28
	v_sub_f32_e32 v28, v76, v60
	v_exp_f32_e32 v28, v28
	v_exp_f32_e32 v76, v65
	v_add_f32_e32 v32, v28, v29
	v_sub_f32_e32 v29, v77, v60
	v_exp_f32_e32 v29, v29
	v_exp_f32_e32 v77, v64
	v_add_f32_e32 v33, v29, v32
	v_sub_f32_e32 v32, v78, v60
	v_exp_f32_e32 v32, v32
	v_exp_f32_e32 v78, v61
	v_add_f32_e32 v38, v32, v33
	v_sub_f32_e32 v33, v79, v60
	v_exp_f32_e32 v33, v33
	v_exp_f32_e32 v79, v0
	v_mov_b32_e32 v0, v1
	v_add_f32_e32 v39, v33, v38
	v_sub_f32_e32 v38, v96, v60
	v_exp_f32_e32 v38, v38
	s_nop 0
	v_add_f32_e32 v40, v38, v39
	v_sub_f32_e32 v39, v97, v60
	v_exp_f32_e32 v39, v39
	s_nop 0
	v_add_f32_e32 v41, v39, v40
	v_sub_f32_e32 v40, v98, v60
	v_exp_f32_e32 v40, v40
	s_nop 0
	v_add_f32_e32 v42, v40, v41
	v_sub_f32_e32 v41, v99, v60
	v_exp_f32_e32 v41, v41
	s_nop 0
	v_add_f32_e32 v43, v41, v42
	v_sub_f32_e32 v42, v100, v60
	v_exp_f32_e32 v42, v42
	s_nop 0
	v_add_f32_e32 v44, v42, v43
	v_sub_f32_e32 v43, v101, v60
	v_exp_f32_e32 v43, v43
	s_nop 0
	v_add_f32_e32 v44, v43, v44
	v_add_f32_e32 v44, v46, v44
	v_add_f32_e32 v44, v47, v44
	v_add_f32_e32 v44, v50, v44
	v_add_f32_e32 v44, v51, v44
	v_add_f32_e32 v44, v52, v44
	v_add_f32_e32 v45, v53, v44
	v_sub_f32_e32 v44, v108, v60
	v_exp_f32_e32 v44, v44
	s_nop 0
	v_add_f32_e32 v48, v44, v45
	v_sub_f32_e32 v45, v109, v60
	v_exp_f32_e32 v45, v45
	s_nop 0
	v_add_f32_e32 v49, v45, v48
	v_sub_f32_e32 v48, v110, v60
	v_exp_f32_e32 v48, v48
	s_nop 0
	v_add_f32_e32 v54, v48, v49
	v_sub_f32_e32 v49, v111, v60
	v_exp_f32_e32 v49, v49
	s_nop 0
	v_add_f32_e32 v55, v49, v54
	v_sub_f32_e32 v54, v129, v60
	v_exp_f32_e32 v54, v54
	s_nop 0
	v_add_f32_e32 v66, v54, v55
	v_sub_f32_e32 v55, v130, v60
	v_exp_f32_e32 v55, v55
	s_nop 0
	v_add_f32_e32 v66, v55, v66
	v_add_f32_e32 v66, v56, v66
	v_add_f32_e32 v66, v57, v66
	v_add_f32_e32 v66, v58, v66
	v_add_f32_e32 v66, v59, v66
	v_add_f32_e32 v66, v62, v66
	v_add_f32_e32 v66, v63, v66
	v_add_f32_e32 v65, v76, v66
	v_add_f32_e32 v64, v77, v65
	v_add_f32_e32 v61, v78, v64
	v_add_f32_e32 v60, v79, v61
	ds_bpermute_b32 v61, v196, v60
	s_and_saveexec_b64 s[0:1], vcc
	s_cbranch_execz .LBB0_946
	s_waitcnt lgkmcnt(0)
	v_add_f32_e32 v0, v60, v61
	v_div_scale_f32 v60, s[26:27], v0, v0, 1.0
	v_rcp_f32_e32 v61, v60
	v_div_scale_f32 v64, vcc, 1.0, v0, 1.0
	v_fma_f32 v65, -v60, v61, 1.0
	v_fmac_f32_e32 v61, v65, v61
	v_mul_f32_e32 v65, v64, v61
	v_fma_f32 v66, -v60, v65, v64
	v_fmac_f32_e32 v65, v66, v61
	v_fma_f32 v60, -v60, v65, v64
	v_div_fmas_f32 v60, v60, v61, v65
	v_div_fixup_f32 v0, v60, v0, 1.0
